# GEMM k-loops: per-segment s_setprio toggles removed, one static s_setprio 1 for the wr==1 wave half per tile loop (lever 4)
# baseline (speedup 1.0000x reference)
.LBB0_173:
	s_and_b64 s[98:99], exec, s[22:23]
	s_cbranch_scc1 .Lsp_173
	s_setprio 1

.LBB0_176:
	s_add_u32 s2, s14, 0xfffc0080
	s_addc_u32 s3, s15, -1
	s_add_i32 s47, 0, 0x10000
	s_cmp_eq_u32 s46, 12
	s_cselect_b32 s25, s7, s3
	s_cselect_b32 s24, s11, s2
	v_add_u32_e32 v0, s47, v155
	s_cselect_b32 s3, s13, s33
	s_cselect_b32 s2, s29, s31
	s_add_i32 s54, 0, 0x14000
	ds_read_b128 v[50:53], v0
	ds_read_b128 v[54:57], v0 offset:1024
	ds_read_b128 v[58:61], v0 offset:2048
	ds_read_b128 v[62:65], v0 offset:3072
	v_add_u32_e32 v0, s54, v155
	ds_read_b128 v[176:179], v0
	ds_read_b128 v[188:191], v0 offset:1024
	ds_read_b128 v[192:195], v0 offset:2048
	ds_read_b128 v[196:199], v0 offset:3072
	v_lshl_add_u64 v[180:181], s[14:15], 0, v[170:171]
	s_add_i32 m0, s90, 0xc000
	ds_read_b128 v[200:203], v186
	ds_read_b128 v[204:207], v186 offset:1024
	ds_read_b128 v[226:229], v186 offset:2048
	ds_read_b128 v[230:233], v186 offset:3072
	ds_read_b128 v[234:237], v186 offset:4096
	ds_read_b128 v[238:241], v186 offset:5120
	ds_read_b128 v[242:245], v186 offset:6144
	ds_read_b128 v[246:249], v186 offset:7168
	global_load_lds_dwordx4 v[180:181], off
	v_lshl_add_u64 v[180:181], s[14:15], 0, v[172:173]
	s_add_i32 m0, s90, 0xe000
	s_nop 0
	global_load_lds_dwordx4 v[180:181], off
	s_waitcnt vmcnt(8)
	s_waitcnt lgkmcnt(0)
	s_barrier
	v_mfma_f32_16x16x32_bf16 v[142:145], v[50:53], v[200:203], v[142:145]
	v_mfma_f32_16x16x32_bf16 v[138:141], v[58:61], v[200:203], v[138:141]
	v_mfma_f32_16x16x32_bf16 v[126:129], v[50:53], v[226:229], v[126:129]
	v_mfma_f32_16x16x32_bf16 v[122:125], v[58:61], v[226:229], v[122:125]
	v_mfma_f32_16x16x32_bf16 v[110:113], v[50:53], v[234:237], v[110:113]
	v_mfma_f32_16x16x32_bf16 v[106:109], v[58:61], v[234:237], v[106:109]
	v_mfma_f32_16x16x32_bf16 v[94:97], v[50:53], v[242:245], v[94:97]
	v_mfma_f32_16x16x32_bf16 v[90:93], v[58:61], v[242:245], v[90:93]
	v_mfma_f32_16x16x32_bf16 v[142:145], v[54:57], v[204:207], v[142:145]
	v_mfma_f32_16x16x32_bf16 v[138:141], v[62:65], v[204:207], v[138:141]
	v_mfma_f32_16x16x32_bf16 v[126:129], v[54:57], v[230:233], v[126:129]
	v_mfma_f32_16x16x32_bf16 v[122:125], v[62:65], v[230:233], v[122:125]
	v_mfma_f32_16x16x32_bf16 v[110:113], v[54:57], v[238:241], v[110:113]
	v_mfma_f32_16x16x32_bf16 v[106:109], v[62:65], v[238:241], v[106:109]
	v_mfma_f32_16x16x32_bf16 v[94:97], v[54:57], v[246:249], v[94:97]
	v_mfma_f32_16x16x32_bf16 v[90:93], v[62:65], v[246:249], v[90:93]
	v_mfma_f32_16x16x32_bf16 v[134:137], v[176:179], v[200:203], v[134:137]
	v_mfma_f32_16x16x32_bf16 v[130:133], v[192:195], v[200:203], v[130:133]
	v_mfma_f32_16x16x32_bf16 v[118:121], v[176:179], v[226:229], v[118:121]
	v_mfma_f32_16x16x32_bf16 v[114:117], v[192:195], v[226:229], v[114:117]
	v_mfma_f32_16x16x32_bf16 v[102:105], v[176:179], v[234:237], v[102:105]
	v_mfma_f32_16x16x32_bf16 v[98:101], v[192:195], v[234:237], v[98:101]
	v_mfma_f32_16x16x32_bf16 v[86:89], v[176:179], v[242:245], v[86:89]
	v_mfma_f32_16x16x32_bf16 v[82:85], v[192:195], v[242:245], v[82:85]
	v_mfma_f32_16x16x32_bf16 v[134:137], v[188:191], v[204:207], v[134:137]
	v_mfma_f32_16x16x32_bf16 v[130:133], v[196:199], v[204:207], v[130:133]
	v_mfma_f32_16x16x32_bf16 v[118:121], v[188:191], v[230:233], v[118:121]
	v_mfma_f32_16x16x32_bf16 v[114:117], v[196:199], v[230:233], v[114:117]
	v_mfma_f32_16x16x32_bf16 v[102:105], v[188:191], v[238:241], v[102:105]
	v_mfma_f32_16x16x32_bf16 v[98:101], v[196:199], v[238:241], v[98:101]
	v_mfma_f32_16x16x32_bf16 v[86:89], v[188:191], v[246:249], v[86:89]
	v_mfma_f32_16x16x32_bf16 v[82:85], v[196:199], v[246:249], v[82:85]
	s_barrier
	s_add_i32 s47, s47, s42
	v_lshl_add_u64 v[180:181], s[2:3], 0, v[146:147]
	s_mov_b32 m0, s47
	ds_read_b128 v[200:203], v186 offset:16384
	ds_read_b128 v[204:207], v186 offset:17408
	ds_read_b128 v[226:229], v186 offset:18432
	ds_read_b128 v[230:233], v186 offset:19456
	ds_read_b128 v[234:237], v186 offset:20480
	ds_read_b128 v[238:241], v186 offset:21504
	ds_read_b128 v[242:245], v186 offset:22528
	ds_read_b128 v[246:249], v186 offset:23552
	global_load_lds_dwordx4 v[180:181], off
	s_add_i32 m0, s47, 0x2000
	s_add_u32 s58, s2, 0x40000
	v_lshl_add_u64 v[222:223], s[2:3], 0, v[148:149]
	s_addc_u32 s59, s3, 0
	s_add_i32 s47, s54, s42
	global_load_lds_dwordx4 v[222:223], off
	v_lshl_add_u64 v[224:225], s[58:59], 0, v[146:147]
	s_mov_b32 m0, s47
	v_lshl_add_u64 v[250:251], s[24:25], 0, v[148:149]
	global_load_lds_dwordx4 v[224:225], off
	v_lshl_add_u64 v[224:225], s[58:59], 0, v[148:149]
	s_add_i32 m0, s47, 0x2000
	s_nop 0
	global_load_lds_dwordx4 v[224:225], off
	v_lshl_add_u64 v[224:225], s[24:25], 0, v[146:147]
	s_mov_b32 m0, s90
	s_nop 0
	global_load_lds_dwordx4 v[224:225], off
	s_mov_b32 m0, s91
	s_nop 0
	global_load_lds_dwordx4 v[250:251], off
	s_waitcnt vmcnt(8)
	s_waitcnt lgkmcnt(0)
	s_barrier
	v_mfma_f32_16x16x32_bf16 v[78:81], v[50:53], v[200:203], v[78:81]
	v_mfma_f32_16x16x32_bf16 v[74:77], v[58:61], v[200:203], v[74:77]
	v_mfma_f32_16x16x32_bf16 v[46:49], v[50:53], v[226:229], v[46:49]
	v_mfma_f32_16x16x32_bf16 v[42:45], v[58:61], v[226:229], v[42:45]
	v_mfma_f32_16x16x32_bf16 v[30:33], v[50:53], v[234:237], v[30:33]
	v_mfma_f32_16x16x32_bf16 v[26:29], v[58:61], v[234:237], v[26:29]
	v_mfma_f32_16x16x32_bf16 v[14:17], v[50:53], v[242:245], v[14:17]
	v_mfma_f32_16x16x32_bf16 v[10:13], v[58:61], v[242:245], v[10:13]
	v_mfma_f32_16x16x32_bf16 v[78:81], v[54:57], v[204:207], v[78:81]
	v_mfma_f32_16x16x32_bf16 v[74:77], v[62:65], v[204:207], v[74:77]
	v_mfma_f32_16x16x32_bf16 v[46:49], v[54:57], v[230:233], v[46:49]
	v_mfma_f32_16x16x32_bf16 v[42:45], v[62:65], v[230:233], v[42:45]
	v_mfma_f32_16x16x32_bf16 v[30:33], v[54:57], v[238:241], v[30:33]
	v_mfma_f32_16x16x32_bf16 v[26:29], v[62:65], v[238:241], v[26:29]
	v_mfma_f32_16x16x32_bf16 v[14:17], v[54:57], v[246:249], v[14:17]
	v_mfma_f32_16x16x32_bf16 v[10:13], v[62:65], v[246:249], v[10:13]
	v_mfma_f32_16x16x32_bf16 v[38:41], v[176:179], v[226:229], v[38:41]
	v_mfma_f32_16x16x32_bf16 v[34:37], v[192:195], v[226:229], v[34:37]
	v_mfma_f32_16x16x32_bf16 v[22:25], v[176:179], v[234:237], v[22:25]
	v_mfma_f32_16x16x32_bf16 v[18:21], v[192:195], v[234:237], v[18:21]
	v_mfma_f32_16x16x32_bf16 v[6:9], v[176:179], v[242:245], v[6:9]
	v_mfma_f32_16x16x32_bf16 v[2:5], v[192:195], v[242:245], v[2:5]
	v_mfma_f32_16x16x32_bf16 v[50:53], v[176:179], v[200:203], v[70:73]
	v_mfma_f32_16x16x32_bf16 v[54:57], v[192:195], v[200:203], v[66:69]
	v_mfma_f32_16x16x32_bf16 v[38:41], v[188:191], v[230:233], v[38:41]
	v_mfma_f32_16x16x32_bf16 v[34:37], v[196:199], v[230:233], v[34:37]
	v_mfma_f32_16x16x32_bf16 v[22:25], v[188:191], v[238:241], v[22:25]
	v_mfma_f32_16x16x32_bf16 v[18:21], v[196:199], v[238:241], v[18:21]
	v_mfma_f32_16x16x32_bf16 v[6:9], v[188:191], v[246:249], v[6:9]
	v_mfma_f32_16x16x32_bf16 v[2:5], v[196:199], v[246:249], v[2:5]
	v_mfma_f32_16x16x32_bf16 v[50:53], v[188:191], v[204:207], v[50:53]
	v_mfma_f32_16x16x32_bf16 v[54:57], v[196:199], v[204:207], v[54:57]
	s_barrier
	s_add_i32 s47, 0, 0x18000
	v_add_u32_e32 v0, s47, v155
	s_add_i32 s54, 0, 0x1c000
	ds_read_b128 v[58:61], v0
	ds_read_b128 v[62:65], v0 offset:1024
	ds_read_b128 v[66:69], v0 offset:2048
	ds_read_b128 v[70:73], v0 offset:3072
	v_add_u32_e32 v0, s54, v155
	ds_read_b128 v[176:179], v0
	ds_read_b128 v[188:191], v0 offset:1024
	ds_read_b128 v[192:195], v0 offset:2048
	ds_read_b128 v[196:199], v0 offset:3072
	s_add_u32 s24, s24, 0x40000
	s_addc_u32 s25, s25, 0
	s_mov_b32 m0, s74
	v_lshl_add_u64 v[218:219], s[24:25], 0, v[146:147]
	ds_read_b128 v[200:203], v186 offset:32768
	ds_read_b128 v[204:207], v186 offset:33792
	ds_read_b128 v[226:229], v186 offset:34816
	ds_read_b128 v[230:233], v186 offset:35840
	ds_read_b128 v[234:237], v186 offset:36864
	ds_read_b128 v[238:241], v186 offset:37888
	ds_read_b128 v[242:245], v186 offset:38912
	ds_read_b128 v[246:249], v186 offset:39936
	global_load_lds_dwordx4 v[218:219], off
	v_lshl_add_u64 v[218:219], s[24:25], 0, v[148:149]
	s_mov_b32 m0, s75
	s_nop 0
	global_load_lds_dwordx4 v[218:219], off
	s_waitcnt vmcnt(8)
	s_waitcnt lgkmcnt(0)
	s_barrier
	v_mfma_f32_16x16x32_bf16 v[142:145], v[58:61], v[200:203], v[142:145]
	v_mfma_f32_16x16x32_bf16 v[138:141], v[66:69], v[200:203], v[138:141]
	v_mfma_f32_16x16x32_bf16 v[126:129], v[58:61], v[226:229], v[126:129]
	v_mfma_f32_16x16x32_bf16 v[122:125], v[66:69], v[226:229], v[122:125]
	v_mfma_f32_16x16x32_bf16 v[110:113], v[58:61], v[234:237], v[110:113]
	v_mfma_f32_16x16x32_bf16 v[106:109], v[66:69], v[234:237], v[106:109]
	v_mfma_f32_16x16x32_bf16 v[94:97], v[58:61], v[242:245], v[94:97]
	v_mfma_f32_16x16x32_bf16 v[90:93], v[66:69], v[242:245], v[90:93]
	v_mfma_f32_16x16x32_bf16 v[142:145], v[62:65], v[204:207], v[142:145]
	v_mfma_f32_16x16x32_bf16 v[138:141], v[70:73], v[204:207], v[138:141]
	v_mfma_f32_16x16x32_bf16 v[126:129], v[62:65], v[230:233], v[126:129]
	v_mfma_f32_16x16x32_bf16 v[122:125], v[70:73], v[230:233], v[122:125]
	v_mfma_f32_16x16x32_bf16 v[110:113], v[62:65], v[238:241], v[110:113]
	v_mfma_f32_16x16x32_bf16 v[106:109], v[70:73], v[238:241], v[106:109]
	v_mfma_f32_16x16x32_bf16 v[94:97], v[62:65], v[246:249], v[94:97]
	v_mfma_f32_16x16x32_bf16 v[90:93], v[70:73], v[246:249], v[90:93]
	v_mfma_f32_16x16x32_bf16 v[134:137], v[176:179], v[200:203], v[134:137]
	v_mfma_f32_16x16x32_bf16 v[130:133], v[192:195], v[200:203], v[130:133]
	v_mfma_f32_16x16x32_bf16 v[118:121], v[176:179], v[226:229], v[118:121]
	v_mfma_f32_16x16x32_bf16 v[114:117], v[192:195], v[226:229], v[114:117]
	v_mfma_f32_16x16x32_bf16 v[102:105], v[176:179], v[234:237], v[102:105]
	v_mfma_f32_16x16x32_bf16 v[98:101], v[192:195], v[234:237], v[98:101]
	v_mfma_f32_16x16x32_bf16 v[86:89], v[176:179], v[242:245], v[86:89]
	v_mfma_f32_16x16x32_bf16 v[82:85], v[192:195], v[242:245], v[82:85]
	v_mfma_f32_16x16x32_bf16 v[134:137], v[188:191], v[204:207], v[134:137]
	v_mfma_f32_16x16x32_bf16 v[130:133], v[196:199], v[204:207], v[130:133]
	v_mfma_f32_16x16x32_bf16 v[118:121], v[188:191], v[230:233], v[118:121]
	v_mfma_f32_16x16x32_bf16 v[114:117], v[196:199], v[230:233], v[114:117]
	v_mfma_f32_16x16x32_bf16 v[102:105], v[188:191], v[238:241], v[102:105]
	v_mfma_f32_16x16x32_bf16 v[98:101], v[196:199], v[238:241], v[98:101]
	v_mfma_f32_16x16x32_bf16 v[86:89], v[188:191], v[246:249], v[86:89]
	v_mfma_f32_16x16x32_bf16 v[82:85], v[196:199], v[246:249], v[82:85]
	s_barrier
	s_add_i32 s24, s47, s42
	v_lshl_add_u64 v[180:181], v[180:181], 0, s[44:45]
	s_mov_b32 m0, s24
	ds_read_b128 v[200:203], v186 offset:49152
	ds_read_b128 v[204:207], v186 offset:50176
	ds_read_b128 v[226:229], v186 offset:51200
	ds_read_b128 v[230:233], v186 offset:52224
	ds_read_b128 v[234:237], v186 offset:53248
	ds_read_b128 v[238:241], v186 offset:54272
	ds_read_b128 v[242:245], v186 offset:55296
	ds_read_b128 v[246:249], v186 offset:56320
	global_load_lds_dwordx4 v[180:181], off
	s_add_i32 m0, s24, 0x2000
	s_add_u32 s2, s2, 0x40080
	v_lshl_add_u64 v[180:181], v[222:223], 0, s[44:45]
	s_addc_u32 s3, s3, 0
	s_add_i32 s24, s54, s42
	global_load_lds_dwordx4 v[180:181], off
	v_lshl_add_u64 v[180:181], s[2:3], 0, v[146:147]
	s_mov_b32 m0, s24
	s_nop 0
	global_load_lds_dwordx4 v[180:181], off
	v_lshl_add_u64 v[180:181], s[2:3], 0, v[148:149]
	s_add_i32 m0, s24, 0x2000
	s_nop 0
	global_load_lds_dwordx4 v[180:181], off
	v_lshl_add_u64 v[180:181], v[224:225], 0, s[44:45]
	s_mov_b32 m0, s20
	s_nop 0
	global_load_lds_dwordx4 v[180:181], off
	v_lshl_add_u64 v[180:181], v[250:251], 0, s[44:45]
	s_mov_b32 m0, s21
	s_nop 0
	global_load_lds_dwordx4 v[180:181], off
	s_waitcnt vmcnt(8)
	s_waitcnt lgkmcnt(0)
	s_barrier
	v_mfma_f32_16x16x32_bf16 v[78:81], v[58:61], v[200:203], v[78:81]
	v_mfma_f32_16x16x32_bf16 v[74:77], v[66:69], v[200:203], v[74:77]
	v_mfma_f32_16x16x32_bf16 v[46:49], v[58:61], v[226:229], v[46:49]
	v_mfma_f32_16x16x32_bf16 v[42:45], v[66:69], v[226:229], v[42:45]
	v_mfma_f32_16x16x32_bf16 v[30:33], v[58:61], v[234:237], v[30:33]
	v_mfma_f32_16x16x32_bf16 v[26:29], v[66:69], v[234:237], v[26:29]
	v_mfma_f32_16x16x32_bf16 v[14:17], v[58:61], v[242:245], v[14:17]
	v_mfma_f32_16x16x32_bf16 v[10:13], v[66:69], v[242:245], v[10:13]
	v_mfma_f32_16x16x32_bf16 v[78:81], v[62:65], v[204:207], v[78:81]
	v_mfma_f32_16x16x32_bf16 v[74:77], v[70:73], v[204:207], v[74:77]
	v_mfma_f32_16x16x32_bf16 v[46:49], v[62:65], v[230:233], v[46:49]
	v_mfma_f32_16x16x32_bf16 v[42:45], v[70:73], v[230:233], v[42:45]
	v_mfma_f32_16x16x32_bf16 v[30:33], v[62:65], v[238:241], v[30:33]
	v_mfma_f32_16x16x32_bf16 v[26:29], v[70:73], v[238:241], v[26:29]
	v_mfma_f32_16x16x32_bf16 v[14:17], v[62:65], v[246:249], v[14:17]
	v_mfma_f32_16x16x32_bf16 v[10:13], v[70:73], v[246:249], v[10:13]
	v_mfma_f32_16x16x32_bf16 v[50:53], v[176:179], v[200:203], v[50:53]
	v_mfma_f32_16x16x32_bf16 v[70:73], v[188:191], v[204:207], v[50:53]
	v_mfma_f32_16x16x32_bf16 v[50:53], v[192:195], v[200:203], v[54:57]
	v_mfma_f32_16x16x32_bf16 v[38:41], v[176:179], v[226:229], v[38:41]
	v_mfma_f32_16x16x32_bf16 v[34:37], v[192:195], v[226:229], v[34:37]
	v_mfma_f32_16x16x32_bf16 v[22:25], v[176:179], v[234:237], v[22:25]
	v_mfma_f32_16x16x32_bf16 v[18:21], v[192:195], v[234:237], v[18:21]
	v_mfma_f32_16x16x32_bf16 v[6:9], v[176:179], v[242:245], v[6:9]
	v_mfma_f32_16x16x32_bf16 v[2:5], v[192:195], v[242:245], v[2:5]
	v_mfma_f32_16x16x32_bf16 v[66:69], v[196:199], v[204:207], v[50:53]
	v_mfma_f32_16x16x32_bf16 v[38:41], v[188:191], v[230:233], v[38:41]
	v_mfma_f32_16x16x32_bf16 v[34:37], v[196:199], v[230:233], v[34:37]
	v_mfma_f32_16x16x32_bf16 v[22:25], v[188:191], v[238:241], v[22:25]
	v_mfma_f32_16x16x32_bf16 v[18:21], v[196:199], v[238:241], v[18:21]
	v_mfma_f32_16x16x32_bf16 v[6:9], v[188:191], v[246:249], v[6:9]
	v_mfma_f32_16x16x32_bf16 v[2:5], v[196:199], v[246:249], v[2:5]
	s_barrier
	s_add_i32 s46, s46, 2
	s_add_u32 s14, s14, 0x100
	s_addc_u32 s15, s15, 0
	s_add_u32 s31, s31, 0x100
	s_addc_u32 s33, s33, 0
	s_cmp_gt_u32 s46, 13
	s_cbranch_scc0 .LBB0_176
	s_and_b64 vcc, exec, s[22:23]
	s_cbranch_vccz .LBB0_179
	s_barrier

.LBB0_355:
	s_setprio 0
	s_waitcnt vmcnt(0)
	v_readlane_b32 s96, v255, 1
	v_readlane_b32 s97, v255, 2
	v_readlane_b32 s92, v253, 34
	v_readlane_b32 s74, v255, 12
	v_readlane_b32 s54, v255, 16
	v_readlane_b32 s58, v255, 15
	s_barrier

.LBB0_647:
	s_and_b64 s[98:99], exec, s[12:13]
	s_cbranch_scc1 .Lsp_647
	s_setprio 1

.LBB0_650:
	s_add_u32 s2, s4, 0x100
	s_addc_u32 s3, s5, 0
	s_add_i32 s49, 0, 0x10000
	s_cmp_eq_u32 s48, 12
	s_cselect_b32 s29, s17, s3
	s_cselect_b32 s28, s25, s2
	v_add_u32_e32 v0, s49, v135
	s_cselect_b32 s27, s15, s47
	s_cselect_b32 s26, s42, s46
	s_add_i32 s50, 0, 0x14000
	ds_read_b128 v[146:149], v0
	ds_read_b128 v[150:153], v0 offset:1024
	ds_read_b128 v[154:157], v0 offset:2048
	ds_read_b128 v[158:161], v0 offset:3072
	v_add_u32_e32 v0, s50, v135
	ds_read_b128 v[162:165], v0
	ds_read_b128 v[166:169], v0 offset:1024
	ds_read_b128 v[170:173], v0 offset:2048
	ds_read_b128 v[174:177], v0 offset:3072
	v_lshl_add_u64 v[142:143], s[4:5], 0, v[138:139]
	s_add_i32 m0, s23, 0xc000
	ds_read_b128 v[178:181], v144
	ds_read_b128 v[182:185], v144 offset:1024
	ds_read_b128 v[186:189], v144 offset:2048
	ds_read_b128 v[190:193], v144 offset:3072
	ds_read_b128 v[194:197], v144 offset:4096
	ds_read_b128 v[198:201], v144 offset:5120
	ds_read_b128 v[202:205], v144 offset:6144
	ds_read_b128 v[222:225], v144 offset:7168
	global_load_lds_dwordx4 v[142:143], off
	v_lshl_add_u64 v[142:143], s[4:5], 0, v[140:141]
	s_add_i32 m0, s23, 0xe000
	s_nop 0
	global_load_lds_dwordx4 v[142:143], off
	s_waitcnt vmcnt(8)
	s_waitcnt lgkmcnt(0)
	s_barrier
	v_mfma_f32_16x16x32_bf16 v[126:129], v[146:149], v[178:181], v[126:129]
	v_mfma_f32_16x16x32_bf16 v[122:125], v[154:157], v[178:181], v[122:125]
	v_mfma_f32_16x16x32_bf16 v[110:113], v[146:149], v[186:189], v[110:113]
	v_mfma_f32_16x16x32_bf16 v[106:109], v[154:157], v[186:189], v[106:109]
	v_mfma_f32_16x16x32_bf16 v[94:97], v[146:149], v[194:197], v[94:97]
	v_mfma_f32_16x16x32_bf16 v[90:93], v[154:157], v[194:197], v[90:93]
	v_mfma_f32_16x16x32_bf16 v[78:81], v[146:149], v[202:205], v[78:81]
	v_mfma_f32_16x16x32_bf16 v[74:77], v[154:157], v[202:205], v[74:77]
	v_mfma_f32_16x16x32_bf16 v[126:129], v[150:153], v[182:185], v[126:129]
	v_mfma_f32_16x16x32_bf16 v[122:125], v[158:161], v[182:185], v[122:125]
	v_mfma_f32_16x16x32_bf16 v[110:113], v[150:153], v[190:193], v[110:113]
	v_mfma_f32_16x16x32_bf16 v[106:109], v[158:161], v[190:193], v[106:109]
	v_mfma_f32_16x16x32_bf16 v[94:97], v[150:153], v[198:201], v[94:97]
	v_mfma_f32_16x16x32_bf16 v[90:93], v[158:161], v[198:201], v[90:93]
	v_mfma_f32_16x16x32_bf16 v[78:81], v[150:153], v[222:225], v[78:81]
	v_mfma_f32_16x16x32_bf16 v[74:77], v[158:161], v[222:225], v[74:77]
	v_mfma_f32_16x16x32_bf16 v[118:121], v[162:165], v[178:181], v[118:121]
	v_mfma_f32_16x16x32_bf16 v[114:117], v[170:173], v[178:181], v[114:117]
	v_mfma_f32_16x16x32_bf16 v[102:105], v[162:165], v[186:189], v[102:105]
	v_mfma_f32_16x16x32_bf16 v[98:101], v[170:173], v[186:189], v[98:101]
	v_mfma_f32_16x16x32_bf16 v[86:89], v[162:165], v[194:197], v[86:89]
	v_mfma_f32_16x16x32_bf16 v[82:85], v[170:173], v[194:197], v[82:85]
	v_mfma_f32_16x16x32_bf16 v[70:73], v[162:165], v[202:205], v[70:73]
	v_mfma_f32_16x16x32_bf16 v[66:69], v[170:173], v[202:205], v[66:69]
	v_mfma_f32_16x16x32_bf16 v[118:121], v[166:169], v[182:185], v[118:121]
	v_mfma_f32_16x16x32_bf16 v[114:117], v[174:177], v[182:185], v[114:117]
	v_mfma_f32_16x16x32_bf16 v[102:105], v[166:169], v[190:193], v[102:105]
	v_mfma_f32_16x16x32_bf16 v[98:101], v[174:177], v[190:193], v[98:101]
	v_mfma_f32_16x16x32_bf16 v[86:89], v[166:169], v[198:201], v[86:89]
	v_mfma_f32_16x16x32_bf16 v[82:85], v[174:177], v[198:201], v[82:85]
	v_mfma_f32_16x16x32_bf16 v[70:73], v[166:169], v[222:225], v[70:73]
	v_mfma_f32_16x16x32_bf16 v[66:69], v[174:177], v[222:225], v[66:69]
	s_barrier
	s_add_i32 s4, s49, s30
	v_lshl_add_u64 v[142:143], s[26:27], 0, v[130:131]
	s_mov_b32 m0, s4
	ds_read_b128 v[178:181], v144 offset:16384
	ds_read_b128 v[182:185], v144 offset:17408
	ds_read_b128 v[186:189], v144 offset:18432
	ds_read_b128 v[190:193], v144 offset:19456
	ds_read_b128 v[194:197], v144 offset:20480
	ds_read_b128 v[198:201], v144 offset:21504
	ds_read_b128 v[202:205], v144 offset:22528
	ds_read_b128 v[222:225], v144 offset:23552
	global_load_lds_dwordx4 v[142:143], off
	s_add_i32 m0, s4, 0x2000
	s_add_u32 s4, s26, 0x40000
	v_lshl_add_u64 v[206:207], s[26:27], 0, v[132:133]
	s_addc_u32 s5, s27, 0
	s_add_i32 s49, s50, s30
	global_load_lds_dwordx4 v[206:207], off
	v_lshl_add_u64 v[218:219], s[4:5], 0, v[130:131]
	s_mov_b32 m0, s49
	v_lshl_add_u64 v[226:227], s[28:29], 0, v[132:133]
	global_load_lds_dwordx4 v[218:219], off
	v_lshl_add_u64 v[218:219], s[4:5], 0, v[132:133]
	s_add_i32 m0, s49, 0x2000
	s_nop 0
	global_load_lds_dwordx4 v[218:219], off
	v_lshl_add_u64 v[218:219], s[28:29], 0, v[130:131]
	s_mov_b32 m0, s23
	s_nop 0
	global_load_lds_dwordx4 v[218:219], off
	s_mov_b32 m0, s31
	s_nop 0
	global_load_lds_dwordx4 v[226:227], off
	s_waitcnt vmcnt(8)
	s_waitcnt lgkmcnt(0)
	s_barrier
	v_mfma_f32_16x16x32_bf16 v[62:65], v[146:149], v[178:181], v[62:65]
	v_mfma_f32_16x16x32_bf16 v[58:61], v[154:157], v[178:181], v[58:61]
	v_mfma_f32_16x16x32_bf16 v[46:49], v[146:149], v[186:189], v[46:49]
	v_mfma_f32_16x16x32_bf16 v[42:45], v[154:157], v[186:189], v[42:45]
	v_mfma_f32_16x16x32_bf16 v[30:33], v[146:149], v[194:197], v[30:33]
	v_mfma_f32_16x16x32_bf16 v[26:29], v[154:157], v[194:197], v[26:29]
	v_mfma_f32_16x16x32_bf16 v[14:17], v[146:149], v[202:205], v[14:17]
	v_mfma_f32_16x16x32_bf16 v[10:13], v[154:157], v[202:205], v[10:13]
	v_mfma_f32_16x16x32_bf16 v[62:65], v[150:153], v[182:185], v[62:65]
	v_mfma_f32_16x16x32_bf16 v[58:61], v[158:161], v[182:185], v[58:61]
	v_mfma_f32_16x16x32_bf16 v[46:49], v[150:153], v[190:193], v[46:49]
	v_mfma_f32_16x16x32_bf16 v[42:45], v[158:161], v[190:193], v[42:45]
	v_mfma_f32_16x16x32_bf16 v[30:33], v[150:153], v[198:201], v[30:33]
	v_mfma_f32_16x16x32_bf16 v[26:29], v[158:161], v[198:201], v[26:29]
	v_mfma_f32_16x16x32_bf16 v[14:17], v[150:153], v[222:225], v[14:17]
	v_mfma_f32_16x16x32_bf16 v[10:13], v[158:161], v[222:225], v[10:13]
	v_mfma_f32_16x16x32_bf16 v[54:57], v[162:165], v[178:181], v[54:57]
	v_mfma_f32_16x16x32_bf16 v[50:53], v[170:173], v[178:181], v[50:53]
	v_mfma_f32_16x16x32_bf16 v[38:41], v[162:165], v[186:189], v[38:41]
	v_mfma_f32_16x16x32_bf16 v[34:37], v[170:173], v[186:189], v[34:37]
	v_mfma_f32_16x16x32_bf16 v[22:25], v[162:165], v[194:197], v[22:25]
	v_mfma_f32_16x16x32_bf16 v[18:21], v[170:173], v[194:197], v[18:21]
	v_mfma_f32_16x16x32_bf16 v[6:9], v[162:165], v[202:205], v[6:9]
	v_mfma_f32_16x16x32_bf16 v[2:5], v[170:173], v[202:205], v[2:5]
	v_mfma_f32_16x16x32_bf16 v[54:57], v[166:169], v[182:185], v[54:57]
	v_mfma_f32_16x16x32_bf16 v[50:53], v[174:177], v[182:185], v[50:53]
	v_mfma_f32_16x16x32_bf16 v[38:41], v[166:169], v[190:193], v[38:41]
	v_mfma_f32_16x16x32_bf16 v[34:37], v[174:177], v[190:193], v[34:37]
	v_mfma_f32_16x16x32_bf16 v[22:25], v[166:169], v[198:201], v[22:25]
	v_mfma_f32_16x16x32_bf16 v[18:21], v[174:177], v[198:201], v[18:21]
	v_mfma_f32_16x16x32_bf16 v[6:9], v[166:169], v[222:225], v[6:9]
	v_mfma_f32_16x16x32_bf16 v[2:5], v[174:177], v[222:225], v[2:5]
	s_barrier
	s_add_i32 s49, 0, 0x18000
	v_add_u32_e32 v0, s49, v135
	s_add_i32 s50, 0, 0x1c000
	ds_read_b128 v[146:149], v0
	ds_read_b128 v[150:153], v0 offset:1024
	ds_read_b128 v[154:157], v0 offset:2048
	ds_read_b128 v[158:161], v0 offset:3072
	v_add_u32_e32 v0, s50, v135
	ds_read_b128 v[162:165], v0
	ds_read_b128 v[166:169], v0 offset:1024
	ds_read_b128 v[170:173], v0 offset:2048
	ds_read_b128 v[174:177], v0 offset:3072
	s_add_u32 s4, s28, 0x40000
	s_addc_u32 s5, s29, 0
	s_mov_b32 m0, s33
	v_lshl_add_u64 v[228:229], s[4:5], 0, v[130:131]
	ds_read_b128 v[178:181], v144 offset:32768
	ds_read_b128 v[182:185], v144 offset:33792
	ds_read_b128 v[186:189], v144 offset:34816
	ds_read_b128 v[190:193], v144 offset:35840
	ds_read_b128 v[194:197], v144 offset:36864
	ds_read_b128 v[198:201], v144 offset:37888
	ds_read_b128 v[202:205], v144 offset:38912
	ds_read_b128 v[222:225], v144 offset:39936
	global_load_lds_dwordx4 v[228:229], off
	v_lshl_add_u64 v[228:229], s[4:5], 0, v[132:133]
	s_mov_b32 m0, s34
	s_nop 0
	global_load_lds_dwordx4 v[228:229], off
	s_waitcnt vmcnt(8)
	s_waitcnt lgkmcnt(0)
	s_barrier
	v_mfma_f32_16x16x32_bf16 v[126:129], v[146:149], v[178:181], v[126:129]
	v_mfma_f32_16x16x32_bf16 v[122:125], v[154:157], v[178:181], v[122:125]
	v_mfma_f32_16x16x32_bf16 v[110:113], v[146:149], v[186:189], v[110:113]
	v_mfma_f32_16x16x32_bf16 v[106:109], v[154:157], v[186:189], v[106:109]
	v_mfma_f32_16x16x32_bf16 v[94:97], v[146:149], v[194:197], v[94:97]
	v_mfma_f32_16x16x32_bf16 v[90:93], v[154:157], v[194:197], v[90:93]
	v_mfma_f32_16x16x32_bf16 v[78:81], v[146:149], v[202:205], v[78:81]
	v_mfma_f32_16x16x32_bf16 v[74:77], v[154:157], v[202:205], v[74:77]
	v_mfma_f32_16x16x32_bf16 v[126:129], v[150:153], v[182:185], v[126:129]
	v_mfma_f32_16x16x32_bf16 v[122:125], v[158:161], v[182:185], v[122:125]
	v_mfma_f32_16x16x32_bf16 v[110:113], v[150:153], v[190:193], v[110:113]
	v_mfma_f32_16x16x32_bf16 v[106:109], v[158:161], v[190:193], v[106:109]
	v_mfma_f32_16x16x32_bf16 v[94:97], v[150:153], v[198:201], v[94:97]
	v_mfma_f32_16x16x32_bf16 v[90:93], v[158:161], v[198:201], v[90:93]
	v_mfma_f32_16x16x32_bf16 v[78:81], v[150:153], v[222:225], v[78:81]
	v_mfma_f32_16x16x32_bf16 v[74:77], v[158:161], v[222:225], v[74:77]
	v_mfma_f32_16x16x32_bf16 v[118:121], v[162:165], v[178:181], v[118:121]
	v_mfma_f32_16x16x32_bf16 v[114:117], v[170:173], v[178:181], v[114:117]
	v_mfma_f32_16x16x32_bf16 v[102:105], v[162:165], v[186:189], v[102:105]
	v_mfma_f32_16x16x32_bf16 v[98:101], v[170:173], v[186:189], v[98:101]
	v_mfma_f32_16x16x32_bf16 v[86:89], v[162:165], v[194:197], v[86:89]
	v_mfma_f32_16x16x32_bf16 v[82:85], v[170:173], v[194:197], v[82:85]
	v_mfma_f32_16x16x32_bf16 v[70:73], v[162:165], v[202:205], v[70:73]
	v_mfma_f32_16x16x32_bf16 v[66:69], v[170:173], v[202:205], v[66:69]
	v_mfma_f32_16x16x32_bf16 v[118:121], v[166:169], v[182:185], v[118:121]
	v_mfma_f32_16x16x32_bf16 v[114:117], v[174:177], v[182:185], v[114:117]
	v_mfma_f32_16x16x32_bf16 v[102:105], v[166:169], v[190:193], v[102:105]
	v_mfma_f32_16x16x32_bf16 v[98:101], v[174:177], v[190:193], v[98:101]
	v_mfma_f32_16x16x32_bf16 v[86:89], v[166:169], v[198:201], v[86:89]
	v_mfma_f32_16x16x32_bf16 v[82:85], v[174:177], v[198:201], v[82:85]
	v_mfma_f32_16x16x32_bf16 v[70:73], v[166:169], v[222:225], v[70:73]
	v_mfma_f32_16x16x32_bf16 v[66:69], v[174:177], v[222:225], v[66:69]
	s_barrier
	s_add_i32 s4, s49, s30
	v_lshl_add_u64 v[142:143], v[142:143], 0, s[44:45]
	s_mov_b32 m0, s4
	ds_read_b128 v[178:181], v144 offset:49152
	ds_read_b128 v[182:185], v144 offset:50176
	ds_read_b128 v[186:189], v144 offset:51200
	ds_read_b128 v[190:193], v144 offset:52224
	ds_read_b128 v[194:197], v144 offset:53248
	ds_read_b128 v[198:201], v144 offset:54272
	ds_read_b128 v[202:205], v144 offset:55296
	ds_read_b128 v[222:225], v144 offset:56320
	global_load_lds_dwordx4 v[142:143], off
	s_add_i32 m0, s4, 0x2000
	s_add_u32 s4, s26, 0x40080
	v_lshl_add_u64 v[142:143], v[206:207], 0, s[44:45]
	s_addc_u32 s5, s27, 0
	s_add_i32 s26, s50, s30
	global_load_lds_dwordx4 v[142:143], off
	v_lshl_add_u64 v[142:143], s[4:5], 0, v[130:131]
	s_mov_b32 m0, s26
	s_nop 0
	global_load_lds_dwordx4 v[142:143], off
	v_lshl_add_u64 v[142:143], s[4:5], 0, v[132:133]
	s_add_i32 m0, s26, 0x2000
	s_nop 0
	global_load_lds_dwordx4 v[142:143], off
	v_lshl_add_u64 v[142:143], v[218:219], 0, s[44:45]
	s_mov_b32 m0, s37
	s_nop 0
	global_load_lds_dwordx4 v[142:143], off
	v_lshl_add_u64 v[142:143], v[226:227], 0, s[44:45]
	s_mov_b32 m0, s38
	s_nop 0
	global_load_lds_dwordx4 v[142:143], off
	s_waitcnt vmcnt(8)
	s_waitcnt lgkmcnt(0)
	s_barrier
	v_mfma_f32_16x16x32_bf16 v[62:65], v[146:149], v[178:181], v[62:65]
	v_mfma_f32_16x16x32_bf16 v[58:61], v[154:157], v[178:181], v[58:61]
	v_mfma_f32_16x16x32_bf16 v[46:49], v[146:149], v[186:189], v[46:49]
	v_mfma_f32_16x16x32_bf16 v[42:45], v[154:157], v[186:189], v[42:45]
	v_mfma_f32_16x16x32_bf16 v[30:33], v[146:149], v[194:197], v[30:33]
	v_mfma_f32_16x16x32_bf16 v[26:29], v[154:157], v[194:197], v[26:29]
	v_mfma_f32_16x16x32_bf16 v[14:17], v[146:149], v[202:205], v[14:17]
	v_mfma_f32_16x16x32_bf16 v[10:13], v[154:157], v[202:205], v[10:13]
	v_mfma_f32_16x16x32_bf16 v[62:65], v[150:153], v[182:185], v[62:65]
	v_mfma_f32_16x16x32_bf16 v[58:61], v[158:161], v[182:185], v[58:61]
	v_mfma_f32_16x16x32_bf16 v[46:49], v[150:153], v[190:193], v[46:49]
	v_mfma_f32_16x16x32_bf16 v[42:45], v[158:161], v[190:193], v[42:45]
	v_mfma_f32_16x16x32_bf16 v[30:33], v[150:153], v[198:201], v[30:33]
	v_mfma_f32_16x16x32_bf16 v[26:29], v[158:161], v[198:201], v[26:29]
	v_mfma_f32_16x16x32_bf16 v[14:17], v[150:153], v[222:225], v[14:17]
	v_mfma_f32_16x16x32_bf16 v[10:13], v[158:161], v[222:225], v[10:13]
	v_mfma_f32_16x16x32_bf16 v[54:57], v[162:165], v[178:181], v[54:57]
	v_mfma_f32_16x16x32_bf16 v[50:53], v[170:173], v[178:181], v[50:53]
	v_mfma_f32_16x16x32_bf16 v[38:41], v[162:165], v[186:189], v[38:41]
	v_mfma_f32_16x16x32_bf16 v[34:37], v[170:173], v[186:189], v[34:37]
	v_mfma_f32_16x16x32_bf16 v[22:25], v[162:165], v[194:197], v[22:25]
	v_mfma_f32_16x16x32_bf16 v[18:21], v[170:173], v[194:197], v[18:21]
	v_mfma_f32_16x16x32_bf16 v[6:9], v[162:165], v[202:205], v[6:9]
	v_mfma_f32_16x16x32_bf16 v[2:5], v[170:173], v[202:205], v[2:5]
	v_mfma_f32_16x16x32_bf16 v[54:57], v[166:169], v[182:185], v[54:57]
	v_mfma_f32_16x16x32_bf16 v[50:53], v[174:177], v[182:185], v[50:53]
	v_mfma_f32_16x16x32_bf16 v[38:41], v[166:169], v[190:193], v[38:41]
	v_mfma_f32_16x16x32_bf16 v[34:37], v[174:177], v[190:193], v[34:37]
	v_mfma_f32_16x16x32_bf16 v[22:25], v[166:169], v[198:201], v[22:25]
	v_mfma_f32_16x16x32_bf16 v[18:21], v[174:177], v[198:201], v[18:21]
	v_mfma_f32_16x16x32_bf16 v[6:9], v[166:169], v[222:225], v[6:9]
	v_mfma_f32_16x16x32_bf16 v[2:5], v[174:177], v[222:225], v[2:5]
	s_barrier
	s_add_i32 s48, s48, 2
	s_add_u32 s46, s46, 0x100
	s_addc_u32 s47, s47, 0
	s_cmp_gt_u32 s48, 13
	s_mov_b64 s[4:5], s[2:3]
	s_cbranch_scc0 .LBB0_650
	s_and_b64 vcc, exec, s[12:13]
	s_cbranch_vccz .LBB0_653
	s_barrier

.LBB0_672:
	s_setprio 0
	s_waitcnt vmcnt(0)
	s_barrier

.LBB0_783:
	s_add_u32 s2, s4, 0xfffc0080
	s_addc_u32 s3, s5, -1
	s_add_i32 s48, 0, 0x10000
	s_cmp_eq_u32 s47, 12
	s_cselect_b32 s27, s17, s3
	s_cselect_b32 s26, s25, s2
	s_cselect_b32 s3, s15, s46
	s_cselect_b32 s2, s41, s42
	s_add_i32 s50, 0, 0x14000
	v_add_u32_e32 v154, s48, v140
	v_add_u32_e32 v170, s50, v140
	ds_read_b128 v[142:145], v154
	ds_read_b128 v[146:149], v154 offset:1024
	ds_read_b128 v[150:153], v154 offset:2048
	ds_read_b128 v[154:157], v154 offset:3072
	ds_read_b128 v[158:161], v170
	ds_read_b128 v[162:165], v170 offset:1024
	ds_read_b128 v[166:169], v170 offset:2048
	ds_read_b128 v[170:173], v170 offset:3072
	v_lshl_add_u64 v[206:207], s[4:5], 0, v[136:137]
	s_add_i32 m0, s23, 0xc000
	ds_read_b128 v[174:177], v141
	ds_read_b128 v[178:181], v141 offset:1024
	ds_read_b128 v[182:185], v141 offset:2048
	ds_read_b128 v[186:189], v141 offset:3072
	ds_read_b128 v[190:193], v141 offset:4096
	ds_read_b128 v[194:197], v141 offset:5120
	ds_read_b128 v[198:201], v141 offset:6144
	ds_read_b128 v[202:205], v141 offset:7168
	global_load_lds_dwordx4 v[206:207], off
	v_lshl_add_u64 v[206:207], s[4:5], 0, v[138:139]
	s_add_i32 m0, s23, 0xe000
	s_nop 0
	global_load_lds_dwordx4 v[206:207], off
	s_waitcnt vmcnt(8)
	s_waitcnt lgkmcnt(0)
	s_barrier
	v_mfma_f32_16x16x32_bf16 v[122:125], v[142:145], v[174:177], v[122:125]
	v_mfma_f32_16x16x32_bf16 v[114:117], v[150:153], v[174:177], v[114:117]
	v_mfma_f32_16x16x32_bf16 v[106:109], v[142:145], v[182:185], v[106:109]
	v_mfma_f32_16x16x32_bf16 v[98:101], v[150:153], v[182:185], v[98:101]
	v_mfma_f32_16x16x32_bf16 v[90:93], v[142:145], v[190:193], v[90:93]
	v_mfma_f32_16x16x32_bf16 v[82:85], v[150:153], v[190:193], v[82:85]
	v_mfma_f32_16x16x32_bf16 v[74:77], v[142:145], v[198:201], v[74:77]
	v_mfma_f32_16x16x32_bf16 v[66:69], v[150:153], v[198:201], v[66:69]
	v_mfma_f32_16x16x32_bf16 v[122:125], v[146:149], v[178:181], v[122:125]
	v_mfma_f32_16x16x32_bf16 v[114:117], v[154:157], v[178:181], v[114:117]
	v_mfma_f32_16x16x32_bf16 v[106:109], v[146:149], v[186:189], v[106:109]
	v_mfma_f32_16x16x32_bf16 v[98:101], v[154:157], v[186:189], v[98:101]
	v_mfma_f32_16x16x32_bf16 v[90:93], v[146:149], v[194:197], v[90:93]
	v_mfma_f32_16x16x32_bf16 v[82:85], v[154:157], v[194:197], v[82:85]
	v_mfma_f32_16x16x32_bf16 v[74:77], v[146:149], v[202:205], v[74:77]
	v_mfma_f32_16x16x32_bf16 v[66:69], v[154:157], v[202:205], v[66:69]
	v_mfma_f32_16x16x32_bf16 v[126:129], v[158:161], v[174:177], v[126:129]
	v_mfma_f32_16x16x32_bf16 v[118:121], v[166:169], v[174:177], v[118:121]
	v_mfma_f32_16x16x32_bf16 v[110:113], v[158:161], v[182:185], v[110:113]
	v_mfma_f32_16x16x32_bf16 v[102:105], v[166:169], v[182:185], v[102:105]
	v_mfma_f32_16x16x32_bf16 v[94:97], v[158:161], v[190:193], v[94:97]
	v_mfma_f32_16x16x32_bf16 v[86:89], v[166:169], v[190:193], v[86:89]
	v_mfma_f32_16x16x32_bf16 v[78:81], v[158:161], v[198:201], v[78:81]
	v_mfma_f32_16x16x32_bf16 v[70:73], v[166:169], v[198:201], v[70:73]
	v_mfma_f32_16x16x32_bf16 v[126:129], v[162:165], v[178:181], v[126:129]
	v_mfma_f32_16x16x32_bf16 v[118:121], v[170:173], v[178:181], v[118:121]
	v_mfma_f32_16x16x32_bf16 v[110:113], v[162:165], v[186:189], v[110:113]
	v_mfma_f32_16x16x32_bf16 v[102:105], v[170:173], v[186:189], v[102:105]
	v_mfma_f32_16x16x32_bf16 v[94:97], v[162:165], v[194:197], v[94:97]
	v_mfma_f32_16x16x32_bf16 v[86:89], v[170:173], v[194:197], v[86:89]
	v_mfma_f32_16x16x32_bf16 v[78:81], v[162:165], v[202:205], v[78:81]
	v_mfma_f32_16x16x32_bf16 v[70:73], v[170:173], v[202:205], v[70:73]
	s_barrier
	s_add_i32 s48, s48, s28
	v_lshl_add_u64 v[206:207], s[2:3], 0, v[132:133]
	s_mov_b32 m0, s48
	ds_read_b128 v[174:177], v141 offset:16384
	ds_read_b128 v[178:181], v141 offset:17408
	ds_read_b128 v[182:185], v141 offset:18432
	ds_read_b128 v[186:189], v141 offset:19456
	ds_read_b128 v[190:193], v141 offset:20480
	ds_read_b128 v[194:197], v141 offset:21504
	ds_read_b128 v[198:201], v141 offset:22528
	ds_read_b128 v[202:205], v141 offset:23552
	global_load_lds_dwordx4 v[206:207], off
	s_add_i32 m0, s48, 0x2000
	s_add_u32 s48, s2, 0x40000
	v_lshl_add_u64 v[218:219], s[2:3], 0, v[130:131]
	s_addc_u32 s49, s3, 0
	s_add_i32 s50, s50, s28
	global_load_lds_dwordx4 v[218:219], off
	v_lshl_add_u64 v[222:223], s[48:49], 0, v[132:133]
	s_mov_b32 m0, s50
	v_lshl_add_u64 v[224:225], s[26:27], 0, v[130:131]
	global_load_lds_dwordx4 v[222:223], off
	v_lshl_add_u64 v[222:223], s[48:49], 0, v[130:131]
	s_add_i32 m0, s50, 0x2000
	s_nop 0
	global_load_lds_dwordx4 v[222:223], off
	v_lshl_add_u64 v[222:223], s[26:27], 0, v[132:133]
	s_mov_b32 m0, s23
	s_nop 0
	global_load_lds_dwordx4 v[222:223], off
	s_mov_b32 m0, s31
	s_nop 0
	global_load_lds_dwordx4 v[224:225], off
	s_waitcnt vmcnt(8)
	s_waitcnt lgkmcnt(0)
	s_barrier
	v_mfma_f32_16x16x32_bf16 v[58:61], v[142:145], v[174:177], v[58:61]
	v_mfma_f32_16x16x32_bf16 v[50:53], v[150:153], v[174:177], v[50:53]
	v_mfma_f32_16x16x32_bf16 v[42:45], v[142:145], v[182:185], v[42:45]
	v_mfma_f32_16x16x32_bf16 v[34:37], v[150:153], v[182:185], v[34:37]
	v_mfma_f32_16x16x32_bf16 v[26:29], v[142:145], v[190:193], v[26:29]
	v_mfma_f32_16x16x32_bf16 v[18:21], v[150:153], v[190:193], v[18:21]
	v_mfma_f32_16x16x32_bf16 v[10:13], v[142:145], v[198:201], v[10:13]
	v_mfma_f32_16x16x32_bf16 v[2:5], v[150:153], v[198:201], v[2:5]
	v_mfma_f32_16x16x32_bf16 v[58:61], v[146:149], v[178:181], v[58:61]
	v_mfma_f32_16x16x32_bf16 v[50:53], v[154:157], v[178:181], v[50:53]
	v_mfma_f32_16x16x32_bf16 v[42:45], v[146:149], v[186:189], v[42:45]
	v_mfma_f32_16x16x32_bf16 v[34:37], v[154:157], v[186:189], v[34:37]
	v_mfma_f32_16x16x32_bf16 v[26:29], v[146:149], v[194:197], v[26:29]
	v_mfma_f32_16x16x32_bf16 v[18:21], v[154:157], v[194:197], v[18:21]
	v_mfma_f32_16x16x32_bf16 v[10:13], v[146:149], v[202:205], v[10:13]
	v_mfma_f32_16x16x32_bf16 v[2:5], v[154:157], v[202:205], v[2:5]
	v_mfma_f32_16x16x32_bf16 v[62:65], v[158:161], v[174:177], v[62:65]
	v_mfma_f32_16x16x32_bf16 v[54:57], v[166:169], v[174:177], v[54:57]
	v_mfma_f32_16x16x32_bf16 v[46:49], v[158:161], v[182:185], v[46:49]
	v_mfma_f32_16x16x32_bf16 v[38:41], v[166:169], v[182:185], v[38:41]
	v_mfma_f32_16x16x32_bf16 v[30:33], v[158:161], v[190:193], v[30:33]
	v_mfma_f32_16x16x32_bf16 v[22:25], v[166:169], v[190:193], v[22:25]
	v_mfma_f32_16x16x32_bf16 v[14:17], v[158:161], v[198:201], v[14:17]
	v_mfma_f32_16x16x32_bf16 v[6:9], v[166:169], v[198:201], v[6:9]
	v_mfma_f32_16x16x32_bf16 v[62:65], v[162:165], v[178:181], v[62:65]
	v_mfma_f32_16x16x32_bf16 v[54:57], v[170:173], v[178:181], v[54:57]
	v_mfma_f32_16x16x32_bf16 v[46:49], v[162:165], v[186:189], v[46:49]
	v_mfma_f32_16x16x32_bf16 v[38:41], v[170:173], v[186:189], v[38:41]
	v_mfma_f32_16x16x32_bf16 v[30:33], v[162:165], v[194:197], v[30:33]
	v_mfma_f32_16x16x32_bf16 v[22:25], v[170:173], v[194:197], v[22:25]
	v_mfma_f32_16x16x32_bf16 v[14:17], v[162:165], v[202:205], v[14:17]
	v_mfma_f32_16x16x32_bf16 v[6:9], v[170:173], v[202:205], v[6:9]
	s_barrier
	s_add_i32 s48, 0, 0x18000
	s_add_i32 s49, 0, 0x1c000
	v_add_u32_e32 v154, s48, v140
	v_add_u32_e32 v170, s49, v140
	ds_read_b128 v[142:145], v154
	ds_read_b128 v[146:149], v154 offset:1024
	ds_read_b128 v[150:153], v154 offset:2048
	ds_read_b128 v[154:157], v154 offset:3072
	ds_read_b128 v[158:161], v170
	ds_read_b128 v[162:165], v170 offset:1024
	ds_read_b128 v[166:169], v170 offset:2048
	ds_read_b128 v[170:173], v170 offset:3072
	s_add_u32 s26, s26, 0x40000
	s_addc_u32 s27, s27, 0
	s_mov_b32 m0, s33
	v_lshl_add_u64 v[226:227], s[26:27], 0, v[132:133]
	ds_read_b128 v[174:177], v141 offset:32768
	ds_read_b128 v[178:181], v141 offset:33792
	ds_read_b128 v[182:185], v141 offset:34816
	ds_read_b128 v[186:189], v141 offset:35840
	ds_read_b128 v[190:193], v141 offset:36864
	ds_read_b128 v[194:197], v141 offset:37888
	ds_read_b128 v[198:201], v141 offset:38912
	ds_read_b128 v[202:205], v141 offset:39936
	global_load_lds_dwordx4 v[226:227], off
	v_lshl_add_u64 v[226:227], s[26:27], 0, v[130:131]
	s_mov_b32 m0, s34
	s_nop 0
	global_load_lds_dwordx4 v[226:227], off
	s_waitcnt vmcnt(8)
	s_waitcnt lgkmcnt(0)
	s_barrier
	v_mfma_f32_16x16x32_bf16 v[122:125], v[142:145], v[174:177], v[122:125]
	v_mfma_f32_16x16x32_bf16 v[114:117], v[150:153], v[174:177], v[114:117]
	v_mfma_f32_16x16x32_bf16 v[106:109], v[142:145], v[182:185], v[106:109]
	v_mfma_f32_16x16x32_bf16 v[98:101], v[150:153], v[182:185], v[98:101]
	v_mfma_f32_16x16x32_bf16 v[90:93], v[142:145], v[190:193], v[90:93]
	v_mfma_f32_16x16x32_bf16 v[82:85], v[150:153], v[190:193], v[82:85]
	v_mfma_f32_16x16x32_bf16 v[74:77], v[142:145], v[198:201], v[74:77]
	v_mfma_f32_16x16x32_bf16 v[66:69], v[150:153], v[198:201], v[66:69]
	v_mfma_f32_16x16x32_bf16 v[122:125], v[146:149], v[178:181], v[122:125]
	v_mfma_f32_16x16x32_bf16 v[114:117], v[154:157], v[178:181], v[114:117]
	v_mfma_f32_16x16x32_bf16 v[106:109], v[146:149], v[186:189], v[106:109]
	v_mfma_f32_16x16x32_bf16 v[98:101], v[154:157], v[186:189], v[98:101]
	v_mfma_f32_16x16x32_bf16 v[90:93], v[146:149], v[194:197], v[90:93]
	v_mfma_f32_16x16x32_bf16 v[82:85], v[154:157], v[194:197], v[82:85]
	v_mfma_f32_16x16x32_bf16 v[74:77], v[146:149], v[202:205], v[74:77]
	v_mfma_f32_16x16x32_bf16 v[66:69], v[154:157], v[202:205], v[66:69]
	v_mfma_f32_16x16x32_bf16 v[126:129], v[158:161], v[174:177], v[126:129]
	v_mfma_f32_16x16x32_bf16 v[118:121], v[166:169], v[174:177], v[118:121]
	v_mfma_f32_16x16x32_bf16 v[110:113], v[158:161], v[182:185], v[110:113]
	v_mfma_f32_16x16x32_bf16 v[102:105], v[166:169], v[182:185], v[102:105]
	v_mfma_f32_16x16x32_bf16 v[94:97], v[158:161], v[190:193], v[94:97]
	v_mfma_f32_16x16x32_bf16 v[86:89], v[166:169], v[190:193], v[86:89]
	v_mfma_f32_16x16x32_bf16 v[78:81], v[158:161], v[198:201], v[78:81]
	v_mfma_f32_16x16x32_bf16 v[70:73], v[166:169], v[198:201], v[70:73]
	v_mfma_f32_16x16x32_bf16 v[126:129], v[162:165], v[178:181], v[126:129]
	v_mfma_f32_16x16x32_bf16 v[118:121], v[170:173], v[178:181], v[118:121]
	v_mfma_f32_16x16x32_bf16 v[110:113], v[162:165], v[186:189], v[110:113]
	v_mfma_f32_16x16x32_bf16 v[102:105], v[170:173], v[186:189], v[102:105]
	v_mfma_f32_16x16x32_bf16 v[94:97], v[162:165], v[194:197], v[94:97]
	v_mfma_f32_16x16x32_bf16 v[86:89], v[170:173], v[194:197], v[86:89]
	v_mfma_f32_16x16x32_bf16 v[78:81], v[162:165], v[202:205], v[78:81]
	v_mfma_f32_16x16x32_bf16 v[70:73], v[170:173], v[202:205], v[70:73]
	s_barrier
	s_add_i32 s26, s48, s28
	v_lshl_add_u64 v[206:207], v[206:207], 0, s[44:45]
	s_mov_b32 m0, s26
	ds_read_b128 v[174:177], v141 offset:49152
	ds_read_b128 v[178:181], v141 offset:50176
	ds_read_b128 v[182:185], v141 offset:51200
	ds_read_b128 v[186:189], v141 offset:52224
	ds_read_b128 v[190:193], v141 offset:53248
	ds_read_b128 v[194:197], v141 offset:54272
	ds_read_b128 v[198:201], v141 offset:55296
	ds_read_b128 v[202:205], v141 offset:56320
	global_load_lds_dwordx4 v[206:207], off
	s_add_i32 m0, s26, 0x2000
	s_add_u32 s2, s2, 0x40080
	v_lshl_add_u64 v[206:207], v[218:219], 0, s[44:45]
	s_addc_u32 s3, s3, 0
	s_add_i32 s26, s49, s28
	global_load_lds_dwordx4 v[206:207], off
	v_lshl_add_u64 v[206:207], s[2:3], 0, v[132:133]
	s_mov_b32 m0, s26
	s_nop 0
	global_load_lds_dwordx4 v[206:207], off
	v_lshl_add_u64 v[206:207], s[2:3], 0, v[130:131]
	s_add_i32 m0, s26, 0x2000
	s_nop 0
	global_load_lds_dwordx4 v[206:207], off
	v_lshl_add_u64 v[206:207], v[222:223], 0, s[44:45]
	s_mov_b32 m0, s35
	s_nop 0
	global_load_lds_dwordx4 v[206:207], off
	v_lshl_add_u64 v[206:207], v[224:225], 0, s[44:45]
	s_mov_b32 m0, s36
	s_nop 0
	global_load_lds_dwordx4 v[206:207], off
	s_waitcnt vmcnt(8)
	s_waitcnt lgkmcnt(0)
	s_barrier
	v_mfma_f32_16x16x32_bf16 v[58:61], v[142:145], v[174:177], v[58:61]
	v_mfma_f32_16x16x32_bf16 v[50:53], v[150:153], v[174:177], v[50:53]
	v_mfma_f32_16x16x32_bf16 v[42:45], v[142:145], v[182:185], v[42:45]
	v_mfma_f32_16x16x32_bf16 v[34:37], v[150:153], v[182:185], v[34:37]
	v_mfma_f32_16x16x32_bf16 v[26:29], v[142:145], v[190:193], v[26:29]
	v_mfma_f32_16x16x32_bf16 v[18:21], v[150:153], v[190:193], v[18:21]
	v_mfma_f32_16x16x32_bf16 v[10:13], v[142:145], v[198:201], v[10:13]
	v_mfma_f32_16x16x32_bf16 v[2:5], v[150:153], v[198:201], v[2:5]
	v_mfma_f32_16x16x32_bf16 v[58:61], v[146:149], v[178:181], v[58:61]
	v_mfma_f32_16x16x32_bf16 v[50:53], v[154:157], v[178:181], v[50:53]
	v_mfma_f32_16x16x32_bf16 v[42:45], v[146:149], v[186:189], v[42:45]
	v_mfma_f32_16x16x32_bf16 v[34:37], v[154:157], v[186:189], v[34:37]
	v_mfma_f32_16x16x32_bf16 v[26:29], v[146:149], v[194:197], v[26:29]
	v_mfma_f32_16x16x32_bf16 v[18:21], v[154:157], v[194:197], v[18:21]
	v_mfma_f32_16x16x32_bf16 v[10:13], v[146:149], v[202:205], v[10:13]
	v_mfma_f32_16x16x32_bf16 v[2:5], v[154:157], v[202:205], v[2:5]
	v_mfma_f32_16x16x32_bf16 v[62:65], v[158:161], v[174:177], v[62:65]
	v_mfma_f32_16x16x32_bf16 v[54:57], v[166:169], v[174:177], v[54:57]
	v_mfma_f32_16x16x32_bf16 v[46:49], v[158:161], v[182:185], v[46:49]
	v_mfma_f32_16x16x32_bf16 v[38:41], v[166:169], v[182:185], v[38:41]
	v_mfma_f32_16x16x32_bf16 v[30:33], v[158:161], v[190:193], v[30:33]
	v_mfma_f32_16x16x32_bf16 v[22:25], v[166:169], v[190:193], v[22:25]
	v_mfma_f32_16x16x32_bf16 v[14:17], v[158:161], v[198:201], v[14:17]
	v_mfma_f32_16x16x32_bf16 v[6:9], v[166:169], v[198:201], v[6:9]
	v_mfma_f32_16x16x32_bf16 v[62:65], v[162:165], v[178:181], v[62:65]
	v_mfma_f32_16x16x32_bf16 v[54:57], v[170:173], v[178:181], v[54:57]
	v_mfma_f32_16x16x32_bf16 v[46:49], v[162:165], v[186:189], v[46:49]
	v_mfma_f32_16x16x32_bf16 v[38:41], v[170:173], v[186:189], v[38:41]
	v_mfma_f32_16x16x32_bf16 v[30:33], v[162:165], v[194:197], v[30:33]
	v_mfma_f32_16x16x32_bf16 v[22:25], v[170:173], v[194:197], v[22:25]
	v_mfma_f32_16x16x32_bf16 v[14:17], v[162:165], v[202:205], v[14:17]
	v_mfma_f32_16x16x32_bf16 v[6:9], v[170:173], v[202:205], v[6:9]
	s_barrier
	s_add_i32 s47, s47, 2
	s_add_u32 s4, s4, 0x100
	s_addc_u32 s5, s5, 0
	s_add_u32 s42, s42, 0x100
	s_addc_u32 s46, s46, 0
	s_cmp_gt_u32 s47, 13
	s_cbranch_scc0 .LBB0_783
	s_and_b64 vcc, exec, s[12:13]
	s_cbranch_vccz .LBB0_786
	s_barrier

.LBB0_849:
	s_add_u32 s2, s18, 0x100
	s_addc_u32 s3, s19, 0
	s_add_i32 s47, 0, 0x10000
	s_cmp_eq_u32 s46, 40
	s_cselect_b32 s23, s9, s3
	s_cselect_b32 s22, s8, s2
	v_add_u32_e32 v0, s47, v135
	s_cselect_b32 s21, s15, s42
	s_cselect_b32 s20, s14, s17
	s_add_i32 s48, 0, 0x14000
	ds_read_b128 v[146:149], v0
	ds_read_b128 v[150:153], v0 offset:1024
	ds_read_b128 v[154:157], v0 offset:2048
	ds_read_b128 v[158:161], v0 offset:3072
	v_add_u32_e32 v0, s48, v135
	ds_read_b128 v[162:165], v0
	ds_read_b128 v[166:169], v0 offset:1024
	ds_read_b128 v[170:173], v0 offset:2048
	ds_read_b128 v[174:177], v0 offset:3072
	v_lshl_add_u64 v[142:143], s[18:19], 0, v[138:139]
	s_add_i32 m0, s25, 0xc000
	ds_read_b128 v[178:181], v144
	ds_read_b128 v[182:185], v144 offset:1024
	ds_read_b128 v[186:189], v144 offset:2048
	ds_read_b128 v[190:193], v144 offset:3072
	ds_read_b128 v[194:197], v144 offset:4096
	ds_read_b128 v[198:201], v144 offset:5120
	ds_read_b128 v[202:205], v144 offset:6144
	ds_read_b128 v[222:225], v144 offset:7168
	global_load_lds_dwordx4 v[142:143], off
	v_lshl_add_u64 v[142:143], s[18:19], 0, v[140:141]
	s_add_i32 m0, s25, 0xe000
	s_nop 0
	global_load_lds_dwordx4 v[142:143], off
	s_waitcnt vmcnt(8)
	s_waitcnt lgkmcnt(0)
	s_barrier
	v_mfma_f32_16x16x32_bf16 v[126:129], v[146:149], v[178:181], v[126:129]
	v_mfma_f32_16x16x32_bf16 v[122:125], v[154:157], v[178:181], v[122:125]
	v_mfma_f32_16x16x32_bf16 v[110:113], v[146:149], v[186:189], v[110:113]
	v_mfma_f32_16x16x32_bf16 v[106:109], v[154:157], v[186:189], v[106:109]
	v_mfma_f32_16x16x32_bf16 v[94:97], v[146:149], v[194:197], v[94:97]
	v_mfma_f32_16x16x32_bf16 v[90:93], v[154:157], v[194:197], v[90:93]
	v_mfma_f32_16x16x32_bf16 v[78:81], v[146:149], v[202:205], v[78:81]
	v_mfma_f32_16x16x32_bf16 v[74:77], v[154:157], v[202:205], v[74:77]
	v_mfma_f32_16x16x32_bf16 v[126:129], v[150:153], v[182:185], v[126:129]
	v_mfma_f32_16x16x32_bf16 v[122:125], v[158:161], v[182:185], v[122:125]
	v_mfma_f32_16x16x32_bf16 v[110:113], v[150:153], v[190:193], v[110:113]
	v_mfma_f32_16x16x32_bf16 v[106:109], v[158:161], v[190:193], v[106:109]
	v_mfma_f32_16x16x32_bf16 v[94:97], v[150:153], v[198:201], v[94:97]
	v_mfma_f32_16x16x32_bf16 v[90:93], v[158:161], v[198:201], v[90:93]
	v_mfma_f32_16x16x32_bf16 v[78:81], v[150:153], v[222:225], v[78:81]
	v_mfma_f32_16x16x32_bf16 v[74:77], v[158:161], v[222:225], v[74:77]
	v_mfma_f32_16x16x32_bf16 v[118:121], v[162:165], v[178:181], v[118:121]
	v_mfma_f32_16x16x32_bf16 v[114:117], v[170:173], v[178:181], v[114:117]
	v_mfma_f32_16x16x32_bf16 v[102:105], v[162:165], v[186:189], v[102:105]
	v_mfma_f32_16x16x32_bf16 v[98:101], v[170:173], v[186:189], v[98:101]
	v_mfma_f32_16x16x32_bf16 v[86:89], v[162:165], v[194:197], v[86:89]
	v_mfma_f32_16x16x32_bf16 v[82:85], v[170:173], v[194:197], v[82:85]
	v_mfma_f32_16x16x32_bf16 v[70:73], v[162:165], v[202:205], v[70:73]
	v_mfma_f32_16x16x32_bf16 v[66:69], v[170:173], v[202:205], v[66:69]
	v_mfma_f32_16x16x32_bf16 v[118:121], v[166:169], v[182:185], v[118:121]
	v_mfma_f32_16x16x32_bf16 v[114:117], v[174:177], v[182:185], v[114:117]
	v_mfma_f32_16x16x32_bf16 v[102:105], v[166:169], v[190:193], v[102:105]
	v_mfma_f32_16x16x32_bf16 v[98:101], v[174:177], v[190:193], v[98:101]
	v_mfma_f32_16x16x32_bf16 v[86:89], v[166:169], v[198:201], v[86:89]
	v_mfma_f32_16x16x32_bf16 v[82:85], v[174:177], v[198:201], v[82:85]
	v_mfma_f32_16x16x32_bf16 v[70:73], v[166:169], v[222:225], v[70:73]
	v_mfma_f32_16x16x32_bf16 v[66:69], v[174:177], v[222:225], v[66:69]
	s_barrier
	s_add_i32 s18, s47, s24
	v_lshl_add_u64 v[142:143], s[20:21], 0, v[130:131]
	s_mov_b32 m0, s18
	ds_read_b128 v[178:181], v144 offset:16384
	ds_read_b128 v[182:185], v144 offset:17408
	ds_read_b128 v[186:189], v144 offset:18432
	ds_read_b128 v[190:193], v144 offset:19456
	ds_read_b128 v[194:197], v144 offset:20480
	ds_read_b128 v[198:201], v144 offset:21504
	ds_read_b128 v[202:205], v144 offset:22528
	ds_read_b128 v[222:225], v144 offset:23552
	global_load_lds_dwordx4 v[142:143], off
	s_add_i32 m0, s18, 0x2000
	s_add_u32 s18, s20, 0xb0000
	v_lshl_add_u64 v[206:207], s[20:21], 0, v[132:133]
	s_addc_u32 s19, s21, 0
	s_add_i32 s47, s48, s24
	global_load_lds_dwordx4 v[206:207], off
	v_lshl_add_u64 v[218:219], s[18:19], 0, v[130:131]
	s_mov_b32 m0, s47
	v_lshl_add_u64 v[226:227], s[22:23], 0, v[132:133]
	global_load_lds_dwordx4 v[218:219], off
	v_lshl_add_u64 v[218:219], s[18:19], 0, v[132:133]
	s_add_i32 m0, s47, 0x2000
	s_nop 0
	global_load_lds_dwordx4 v[218:219], off
	v_lshl_add_u64 v[218:219], s[22:23], 0, v[130:131]
	s_mov_b32 m0, s25
	s_nop 0
	global_load_lds_dwordx4 v[218:219], off
	s_mov_b32 m0, s26
	s_nop 0
	global_load_lds_dwordx4 v[226:227], off
	s_waitcnt vmcnt(8)
	s_waitcnt lgkmcnt(0)
	s_barrier
	v_mfma_f32_16x16x32_bf16 v[62:65], v[146:149], v[178:181], v[62:65]
	v_mfma_f32_16x16x32_bf16 v[58:61], v[154:157], v[178:181], v[58:61]
	v_mfma_f32_16x16x32_bf16 v[46:49], v[146:149], v[186:189], v[46:49]
	v_mfma_f32_16x16x32_bf16 v[42:45], v[154:157], v[186:189], v[42:45]
	v_mfma_f32_16x16x32_bf16 v[30:33], v[146:149], v[194:197], v[30:33]
	v_mfma_f32_16x16x32_bf16 v[26:29], v[154:157], v[194:197], v[26:29]
	v_mfma_f32_16x16x32_bf16 v[14:17], v[146:149], v[202:205], v[14:17]
	v_mfma_f32_16x16x32_bf16 v[10:13], v[154:157], v[202:205], v[10:13]
	v_mfma_f32_16x16x32_bf16 v[62:65], v[150:153], v[182:185], v[62:65]
	v_mfma_f32_16x16x32_bf16 v[58:61], v[158:161], v[182:185], v[58:61]
	v_mfma_f32_16x16x32_bf16 v[46:49], v[150:153], v[190:193], v[46:49]
	v_mfma_f32_16x16x32_bf16 v[42:45], v[158:161], v[190:193], v[42:45]
	v_mfma_f32_16x16x32_bf16 v[30:33], v[150:153], v[198:201], v[30:33]
	v_mfma_f32_16x16x32_bf16 v[26:29], v[158:161], v[198:201], v[26:29]
	v_mfma_f32_16x16x32_bf16 v[14:17], v[150:153], v[222:225], v[14:17]
	v_mfma_f32_16x16x32_bf16 v[10:13], v[158:161], v[222:225], v[10:13]
	v_mfma_f32_16x16x32_bf16 v[54:57], v[162:165], v[178:181], v[54:57]
	v_mfma_f32_16x16x32_bf16 v[50:53], v[170:173], v[178:181], v[50:53]
	v_mfma_f32_16x16x32_bf16 v[38:41], v[162:165], v[186:189], v[38:41]
	v_mfma_f32_16x16x32_bf16 v[34:37], v[170:173], v[186:189], v[34:37]
	v_mfma_f32_16x16x32_bf16 v[22:25], v[162:165], v[194:197], v[22:25]
	v_mfma_f32_16x16x32_bf16 v[18:21], v[170:173], v[194:197], v[18:21]
	v_mfma_f32_16x16x32_bf16 v[6:9], v[162:165], v[202:205], v[6:9]
	v_mfma_f32_16x16x32_bf16 v[2:5], v[170:173], v[202:205], v[2:5]
	v_mfma_f32_16x16x32_bf16 v[54:57], v[166:169], v[182:185], v[54:57]
	v_mfma_f32_16x16x32_bf16 v[50:53], v[174:177], v[182:185], v[50:53]
	v_mfma_f32_16x16x32_bf16 v[38:41], v[166:169], v[190:193], v[38:41]
	v_mfma_f32_16x16x32_bf16 v[34:37], v[174:177], v[190:193], v[34:37]
	v_mfma_f32_16x16x32_bf16 v[22:25], v[166:169], v[198:201], v[22:25]
	v_mfma_f32_16x16x32_bf16 v[18:21], v[174:177], v[198:201], v[18:21]
	v_mfma_f32_16x16x32_bf16 v[6:9], v[166:169], v[222:225], v[6:9]
	v_mfma_f32_16x16x32_bf16 v[2:5], v[174:177], v[222:225], v[2:5]
	s_barrier
	s_add_i32 s47, 0, 0x18000
	v_add_u32_e32 v0, s47, v135
	s_add_i32 s48, 0, 0x1c000
	ds_read_b128 v[146:149], v0
	ds_read_b128 v[150:153], v0 offset:1024
	ds_read_b128 v[154:157], v0 offset:2048
	ds_read_b128 v[158:161], v0 offset:3072
	v_add_u32_e32 v0, s48, v135
	ds_read_b128 v[162:165], v0
	ds_read_b128 v[166:169], v0 offset:1024
	ds_read_b128 v[170:173], v0 offset:2048
	ds_read_b128 v[174:177], v0 offset:3072
	s_add_u32 s18, s22, 0xb0000
	s_addc_u32 s19, s23, 0
	s_mov_b32 m0, s27
	v_lshl_add_u64 v[228:229], s[18:19], 0, v[130:131]
	ds_read_b128 v[178:181], v144 offset:32768
	ds_read_b128 v[182:185], v144 offset:33792
	ds_read_b128 v[186:189], v144 offset:34816
	ds_read_b128 v[190:193], v144 offset:35840
	ds_read_b128 v[194:197], v144 offset:36864
	ds_read_b128 v[198:201], v144 offset:37888
	ds_read_b128 v[202:205], v144 offset:38912
	ds_read_b128 v[222:225], v144 offset:39936
	global_load_lds_dwordx4 v[228:229], off
	v_lshl_add_u64 v[228:229], s[18:19], 0, v[132:133]
	s_mov_b32 m0, s28
	s_nop 0
	global_load_lds_dwordx4 v[228:229], off
	s_waitcnt vmcnt(8)
	s_waitcnt lgkmcnt(0)
	s_barrier
	v_mfma_f32_16x16x32_bf16 v[126:129], v[146:149], v[178:181], v[126:129]
	v_mfma_f32_16x16x32_bf16 v[122:125], v[154:157], v[178:181], v[122:125]
	v_mfma_f32_16x16x32_bf16 v[110:113], v[146:149], v[186:189], v[110:113]
	v_mfma_f32_16x16x32_bf16 v[106:109], v[154:157], v[186:189], v[106:109]
	v_mfma_f32_16x16x32_bf16 v[94:97], v[146:149], v[194:197], v[94:97]
	v_mfma_f32_16x16x32_bf16 v[90:93], v[154:157], v[194:197], v[90:93]
	v_mfma_f32_16x16x32_bf16 v[78:81], v[146:149], v[202:205], v[78:81]
	v_mfma_f32_16x16x32_bf16 v[74:77], v[154:157], v[202:205], v[74:77]
	v_mfma_f32_16x16x32_bf16 v[126:129], v[150:153], v[182:185], v[126:129]
	v_mfma_f32_16x16x32_bf16 v[122:125], v[158:161], v[182:185], v[122:125]
	v_mfma_f32_16x16x32_bf16 v[110:113], v[150:153], v[190:193], v[110:113]
	v_mfma_f32_16x16x32_bf16 v[106:109], v[158:161], v[190:193], v[106:109]
	v_mfma_f32_16x16x32_bf16 v[94:97], v[150:153], v[198:201], v[94:97]
	v_mfma_f32_16x16x32_bf16 v[90:93], v[158:161], v[198:201], v[90:93]
	v_mfma_f32_16x16x32_bf16 v[78:81], v[150:153], v[222:225], v[78:81]
	v_mfma_f32_16x16x32_bf16 v[74:77], v[158:161], v[222:225], v[74:77]
	v_mfma_f32_16x16x32_bf16 v[118:121], v[162:165], v[178:181], v[118:121]
	v_mfma_f32_16x16x32_bf16 v[114:117], v[170:173], v[178:181], v[114:117]
	v_mfma_f32_16x16x32_bf16 v[102:105], v[162:165], v[186:189], v[102:105]
	v_mfma_f32_16x16x32_bf16 v[98:101], v[170:173], v[186:189], v[98:101]
	v_mfma_f32_16x16x32_bf16 v[86:89], v[162:165], v[194:197], v[86:89]
	v_mfma_f32_16x16x32_bf16 v[82:85], v[170:173], v[194:197], v[82:85]
	v_mfma_f32_16x16x32_bf16 v[70:73], v[162:165], v[202:205], v[70:73]
	v_mfma_f32_16x16x32_bf16 v[66:69], v[170:173], v[202:205], v[66:69]
	v_mfma_f32_16x16x32_bf16 v[118:121], v[166:169], v[182:185], v[118:121]
	v_mfma_f32_16x16x32_bf16 v[114:117], v[174:177], v[182:185], v[114:117]
	v_mfma_f32_16x16x32_bf16 v[102:105], v[166:169], v[190:193], v[102:105]
	v_mfma_f32_16x16x32_bf16 v[98:101], v[174:177], v[190:193], v[98:101]
	v_mfma_f32_16x16x32_bf16 v[86:89], v[166:169], v[198:201], v[86:89]
	v_mfma_f32_16x16x32_bf16 v[82:85], v[174:177], v[198:201], v[82:85]
	v_mfma_f32_16x16x32_bf16 v[70:73], v[166:169], v[222:225], v[70:73]
	v_mfma_f32_16x16x32_bf16 v[66:69], v[174:177], v[222:225], v[66:69]
	s_barrier
	s_add_i32 s18, s47, s24
	v_lshl_add_u64 v[142:143], v[142:143], 0, s[44:45]
	s_mov_b32 m0, s18
	ds_read_b128 v[178:181], v144 offset:49152
	ds_read_b128 v[182:185], v144 offset:50176
	ds_read_b128 v[186:189], v144 offset:51200
	ds_read_b128 v[190:193], v144 offset:52224
	ds_read_b128 v[194:197], v144 offset:53248
	ds_read_b128 v[198:201], v144 offset:54272
	ds_read_b128 v[202:205], v144 offset:55296
	ds_read_b128 v[222:225], v144 offset:56320
	global_load_lds_dwordx4 v[142:143], off
	s_add_i32 m0, s18, 0x2000
	s_add_u32 s18, s20, 0xb0080
	v_lshl_add_u64 v[142:143], v[206:207], 0, s[44:45]
	s_addc_u32 s19, s21, 0
	s_add_i32 s20, s48, s24
	global_load_lds_dwordx4 v[142:143], off
	v_lshl_add_u64 v[142:143], s[18:19], 0, v[130:131]
	s_mov_b32 m0, s20
	s_nop 0
	global_load_lds_dwordx4 v[142:143], off
	v_lshl_add_u64 v[142:143], s[18:19], 0, v[132:133]
	s_add_i32 m0, s20, 0x2000
	s_nop 0
	global_load_lds_dwordx4 v[142:143], off
	v_lshl_add_u64 v[142:143], v[218:219], 0, s[44:45]
	s_mov_b32 m0, s31
	s_nop 0
	global_load_lds_dwordx4 v[142:143], off
	v_lshl_add_u64 v[142:143], v[226:227], 0, s[44:45]
	s_mov_b32 m0, s33
	s_nop 0
	global_load_lds_dwordx4 v[142:143], off
	s_waitcnt vmcnt(8)
	s_waitcnt lgkmcnt(0)
	s_barrier
	v_mfma_f32_16x16x32_bf16 v[62:65], v[146:149], v[178:181], v[62:65]
	v_mfma_f32_16x16x32_bf16 v[58:61], v[154:157], v[178:181], v[58:61]
	v_mfma_f32_16x16x32_bf16 v[46:49], v[146:149], v[186:189], v[46:49]
	v_mfma_f32_16x16x32_bf16 v[42:45], v[154:157], v[186:189], v[42:45]
	v_mfma_f32_16x16x32_bf16 v[30:33], v[146:149], v[194:197], v[30:33]
	v_mfma_f32_16x16x32_bf16 v[26:29], v[154:157], v[194:197], v[26:29]
	v_mfma_f32_16x16x32_bf16 v[14:17], v[146:149], v[202:205], v[14:17]
	v_mfma_f32_16x16x32_bf16 v[10:13], v[154:157], v[202:205], v[10:13]
	v_mfma_f32_16x16x32_bf16 v[62:65], v[150:153], v[182:185], v[62:65]
	v_mfma_f32_16x16x32_bf16 v[58:61], v[158:161], v[182:185], v[58:61]
	v_mfma_f32_16x16x32_bf16 v[46:49], v[150:153], v[190:193], v[46:49]
	v_mfma_f32_16x16x32_bf16 v[42:45], v[158:161], v[190:193], v[42:45]
	v_mfma_f32_16x16x32_bf16 v[30:33], v[150:153], v[198:201], v[30:33]
	v_mfma_f32_16x16x32_bf16 v[26:29], v[158:161], v[198:201], v[26:29]
	v_mfma_f32_16x16x32_bf16 v[14:17], v[150:153], v[222:225], v[14:17]
	v_mfma_f32_16x16x32_bf16 v[10:13], v[158:161], v[222:225], v[10:13]
	v_mfma_f32_16x16x32_bf16 v[54:57], v[162:165], v[178:181], v[54:57]
	v_mfma_f32_16x16x32_bf16 v[50:53], v[170:173], v[178:181], v[50:53]
	v_mfma_f32_16x16x32_bf16 v[38:41], v[162:165], v[186:189], v[38:41]
	v_mfma_f32_16x16x32_bf16 v[34:37], v[170:173], v[186:189], v[34:37]
	v_mfma_f32_16x16x32_bf16 v[22:25], v[162:165], v[194:197], v[22:25]
	v_mfma_f32_16x16x32_bf16 v[18:21], v[170:173], v[194:197], v[18:21]
	v_mfma_f32_16x16x32_bf16 v[6:9], v[162:165], v[202:205], v[6:9]
	v_mfma_f32_16x16x32_bf16 v[2:5], v[170:173], v[202:205], v[2:5]
	v_mfma_f32_16x16x32_bf16 v[54:57], v[166:169], v[182:185], v[54:57]
	v_mfma_f32_16x16x32_bf16 v[50:53], v[174:177], v[182:185], v[50:53]
	v_mfma_f32_16x16x32_bf16 v[38:41], v[166:169], v[190:193], v[38:41]
	v_mfma_f32_16x16x32_bf16 v[34:37], v[174:177], v[190:193], v[34:37]
	v_mfma_f32_16x16x32_bf16 v[22:25], v[166:169], v[198:201], v[22:25]
	v_mfma_f32_16x16x32_bf16 v[18:21], v[174:177], v[198:201], v[18:21]
	v_mfma_f32_16x16x32_bf16 v[6:9], v[166:169], v[222:225], v[6:9]
	v_mfma_f32_16x16x32_bf16 v[2:5], v[174:177], v[222:225], v[2:5]
	s_barrier
	s_add_i32 s46, s46, 2
	s_add_u32 s17, s17, 0x100
	s_addc_u32 s42, s42, 0
	s_cmp_gt_u32 s46, 41
	s_mov_b64 s[18:19], s[2:3]
	s_cbranch_scc0 .LBB0_849
	s_and_b64 vcc, exec, s[12:13]
	s_cbranch_vccz .LBB0_852
	s_barrier
